# scan loop head: deferred state-update MFMAs interleaved with the issue of the first fragment reads (MFMA/LDS interleave at the loop edge)
# speedup vs baseline: 1.0045x; 1.0045x over previous
.LBB0_1548:
	ds_read_b128 v[52:55], v51 offset:0
	ds_read_b128 v[56:59], v51 offset:16384
	ds_read_b128 v[60:63], v51 offset:4096
	ds_read_b128 v[64:67], v51 offset:20480
	v_mfma_f32_16x16x32_bf16 v[16:19], v[160:163], v[216:219], v[16:19]
	ds_read_b128 v[68:71], v51 offset:8192
	ds_read_b128 v[72:75], v51 offset:24576
	v_mfma_f32_16x16x32_bf16 v[16:19], v[164:167], v[220:223], v[16:19]
	v_cvt_pk_bf16_f32 v40, v8, v9
	ds_read_b128 v[76:79], v51 offset:12288
	ds_read_b128 v[80:83], v51 offset:28672
	v_mfma_f32_16x16x32_bf16 v[20:23], v[172:175], v[216:219], v[20:23]
	ds_read_b128 v[116:119], v50 offset:57344
	ds_read_b128 v[208:211], v50 offset:57360
	v_mfma_f32_16x16x32_bf16 v[20:23], v[248:251], v[220:223], v[20:23]
	v_cvt_pk_bf16_f32 v41, v10, v11
	ds_read_b32 v212, v214
	ds_read_b128 v[84:87], v51 offset:1024
	v_mfma_f32_16x16x32_bf16 v[24:27], v[232:235], v[216:219], v[24:27]
	ds_read_b128 v[88:91], v51 offset:17408
	ds_read_b128 v[92:95], v51 offset:5120
	v_mfma_f32_16x16x32_bf16 v[24:27], v[236:239], v[220:223], v[24:27]
	v_cvt_pk_bf16_f32 v42, v12, v13
	ds_read_b128 v[96:99], v51 offset:21504
	v_mfma_f32_16x16x32_bf16 v[28:31], v[240:243], v[216:219], v[28:31]
	v_mfma_f32_16x16x32_bf16 v[28:31], v[244:247], v[220:223], v[28:31]
	v_cvt_pk_bf16_f32 v43, v14, v15
	s_waitcnt lgkmcnt(14)
	v_mfma_f32_16x16x32_bf16 v[176:179], v[52:55], v[44:47], 0
	ds_read_b128 v[100:103], v51 offset:9216
	s_waitcnt lgkmcnt(14)
	v_mfma_f32_16x16x32_bf16 v[192:195], v[56:59], v[44:47], 0
	ds_read_b128 v[104:107], v51 offset:25600
	s_waitcnt lgkmcnt(14)
	v_mfma_f32_16x16x32_bf16 v[180:183], v[60:63], v[44:47], 0
	ds_read_b128 v[108:111], v51 offset:13312
	v_cvt_pk_bf16_f32 v36, v16, v17
	v_cvt_pk_bf16_f32 v37, v18, v19
	s_waitcnt lgkmcnt(14)
	v_mfma_f32_16x16x32_bf16 v[196:199], v[64:67], v[44:47], 0
	ds_read_b128 v[112:115], v51 offset:29696
	v_cvt_pk_bf16_f32 v38, v20, v21
	v_cvt_pk_bf16_f32 v39, v22, v23
	s_waitcnt lgkmcnt(14)
	v_mfma_f32_16x16x32_bf16 v[184:187], v[68:71], v[44:47], 0
	v_cvt_pk_bf16_f32 v32, v24, v25
	v_cvt_pk_bf16_f32 v33, v26, v27
	s_waitcnt lgkmcnt(13)
	v_mfma_f32_16x16x32_bf16 v[200:203], v[72:75], v[44:47], 0
	v_cvt_pk_bf16_f32 v34, v28, v29
	v_cvt_pk_bf16_f32 v35, v30, v31
	s_waitcnt lgkmcnt(12)
	v_mfma_f32_16x16x32_bf16 v[188:191], v[76:79], v[44:47], 0
	s_waitcnt lgkmcnt(10)
	v_lshlrev_b32_e32 v232, 16, v116
	v_and_b32_e32 v233, 0xffff0000, v116
	v_mfma_f32_16x16x32_bf16 v[204:207], v[80:83], v[44:47], 0
	v_lshlrev_b32_e32 v234, 16, v117
	v_and_b32_e32 v235, 0xffff0000, v117
	ds_read_b128 v[128:131], v51 offset:2048
	ds_read_b128 v[132:135], v51 offset:18432
	ds_read_b128 v[136:139], v51 offset:6144
	ds_read_b128 v[140:143], v51 offset:22528
	s_waitcnt lgkmcnt(11)
	v_mfma_f32_16x16x32_bf16 v[176:179], v[84:87], v[40:43], v[176:179]
	ds_read_b128 v[144:147], v51 offset:10240
	v_lshlrev_b32_e32 v236, 16, v118
	v_and_b32_e32 v237, 0xffff0000, v118
	s_waitcnt lgkmcnt(11)
	v_mfma_f32_16x16x32_bf16 v[192:195], v[88:91], v[40:43], v[192:195]
	ds_read_b128 v[148:151], v51 offset:26624
	v_lshlrev_b32_e32 v238, 16, v119
	v_and_b32_e32 v239, 0xffff0000, v119
	s_waitcnt lgkmcnt(11)
	v_mfma_f32_16x16x32_bf16 v[180:183], v[92:95], v[40:43], v[180:183]
	ds_read_b128 v[152:155], v51 offset:14336
	v_lshlrev_b32_e32 v240, 16, v208
	v_and_b32_e32 v241, 0xffff0000, v208
	s_waitcnt lgkmcnt(11)
	v_mfma_f32_16x16x32_bf16 v[196:199], v[96:99], v[40:43], v[196:199]
	ds_read_b128 v[156:159], v51 offset:30720
	v_lshlrev_b32_e32 v242, 16, v209
	v_and_b32_e32 v243, 0xffff0000, v209
	s_waitcnt lgkmcnt(11)
	v_mfma_f32_16x16x32_bf16 v[184:187], v[100:103], v[40:43], v[184:187]
	v_lshlrev_b32_e32 v244, 16, v210
	v_and_b32_e32 v245, 0xffff0000, v210
	s_waitcnt lgkmcnt(10)
	v_mfma_f32_16x16x32_bf16 v[200:203], v[104:107], v[40:43], v[200:203]
	v_lshlrev_b32_e32 v246, 16, v211
	v_and_b32_e32 v247, 0xffff0000, v211
	s_waitcnt lgkmcnt(9)
	v_mfma_f32_16x16x32_bf16 v[188:191], v[108:111], v[40:43], v[188:191]
	v_mul_f32_e32 v0, v212, v0
	v_mul_f32_e32 v1, v212, v1
	s_waitcnt lgkmcnt(8)
	v_mfma_f32_16x16x32_bf16 v[204:207], v[112:115], v[40:43], v[204:207]
	v_mul_f32_e32 v2, v212, v2
	v_mul_f32_e32 v3, v212, v3
	ds_read_b128 v[52:55], v51 offset:3072
	ds_read_b128 v[56:59], v51 offset:7168
	ds_read_b128 v[60:63], v51 offset:11264
	ds_read_b128 v[64:67], v51 offset:15360
	s_waitcnt lgkmcnt(11)
	v_mfma_f32_16x16x32_bf16 v[176:179], v[128:131], v[36:39], v[176:179]
	ds_read_b128 v[68:71], v51 offset:19456
	v_mul_f32_e32 v4, v212, v4
	v_mul_f32_e32 v5, v212, v5
	s_waitcnt lgkmcnt(11)
	v_mfma_f32_16x16x32_bf16 v[192:195], v[132:135], v[36:39], v[192:195]
	ds_read_b128 v[72:75], v51 offset:23552
	v_mul_f32_e32 v6, v212, v6
	v_mul_f32_e32 v7, v212, v7
	s_waitcnt lgkmcnt(11)
	v_mfma_f32_16x16x32_bf16 v[180:183], v[136:139], v[36:39], v[180:183]
	ds_read_b128 v[76:79], v51 offset:27648
	v_mul_f32_e32 v8, v212, v8
	v_mul_f32_e32 v9, v212, v9
	s_waitcnt lgkmcnt(11)
	v_mfma_f32_16x16x32_bf16 v[196:199], v[140:143], v[36:39], v[196:199]
	ds_read_b128 v[80:83], v51 offset:31744
	v_mul_f32_e32 v10, v212, v10
	v_mul_f32_e32 v11, v212, v11
	s_waitcnt lgkmcnt(11)
	v_mfma_f32_16x16x32_bf16 v[184:187], v[144:147], v[36:39], v[184:187]
	v_mul_f32_e32 v12, v212, v12
	v_mul_f32_e32 v13, v212, v13
	s_waitcnt lgkmcnt(10)
	v_mfma_f32_16x16x32_bf16 v[200:203], v[148:151], v[36:39], v[200:203]
	v_mul_f32_e32 v14, v212, v14
	v_mul_f32_e32 v15, v212, v15
	s_waitcnt lgkmcnt(9)
	v_mfma_f32_16x16x32_bf16 v[188:191], v[152:155], v[36:39], v[188:191]
	v_mul_f32_e32 v16, v212, v16
	v_mul_f32_e32 v17, v212, v17
	s_waitcnt lgkmcnt(8)
	v_mfma_f32_16x16x32_bf16 v[204:207], v[156:159], v[36:39], v[204:207]
	v_mul_f32_e32 v18, v212, v18
	v_mul_f32_e32 v19, v212, v19
	ds_read_b128 v[84:87], v51 offset:49152
	ds_read_b128 v[88:91], v51 offset:51200
	ds_read_b128 v[92:95], v51 offset:53248
	ds_read_b128 v[96:99], v51 offset:55296
	s_waitcnt lgkmcnt(11)
	v_mfma_f32_16x16x32_bf16 v[176:179], v[52:55], v[32:35], v[176:179]
	ds_read_b128 v[100:103], v51 offset:50176
	v_mul_f32_e32 v20, v212, v20
	v_mul_f32_e32 v21, v212, v21
	v_mul_f32_e32 v22, v212, v22
	s_waitcnt lgkmcnt(11)
	v_mfma_f32_16x16x32_bf16 v[180:183], v[56:59], v[32:35], v[180:183]
	ds_read_b128 v[104:107], v51 offset:52224
	v_mul_f32_e32 v23, v212, v23
	v_mul_f32_e32 v24, v212, v24
	v_mul_f32_e32 v25, v212, v25
	s_waitcnt lgkmcnt(11)
	v_mfma_f32_16x16x32_bf16 v[184:187], v[60:63], v[32:35], v[184:187]
	ds_read_b128 v[108:111], v51 offset:54272
	v_mul_f32_e32 v26, v212, v26
	v_mul_f32_e32 v27, v212, v27
	v_mul_f32_e32 v28, v212, v28
	s_waitcnt lgkmcnt(11)
	v_mfma_f32_16x16x32_bf16 v[188:191], v[64:67], v[32:35], v[188:191]
	ds_read_b128 v[112:115], v51 offset:56320
	v_mul_f32_e32 v29, v212, v29
	v_mul_f32_e32 v30, v212, v30
	v_mul_f32_e32 v31, v212, v31
	s_waitcnt lgkmcnt(11)
	v_mfma_f32_16x16x32_bf16 v[192:195], v[68:71], v[32:35], v[192:195]
	v_sub_f32_e32 v232, v232, v176
	v_sub_f32_e32 v233, v233, v177
	v_sub_f32_e32 v234, v234, v178
	v_sub_f32_e32 v235, v235, v179
	s_waitcnt lgkmcnt(10)
	v_mfma_f32_16x16x32_bf16 v[196:199], v[72:75], v[32:35], v[196:199]
	v_sub_f32_e32 v236, v236, v180
	v_sub_f32_e32 v237, v237, v181
	v_sub_f32_e32 v238, v238, v182
	v_sub_f32_e32 v239, v239, v183
	s_waitcnt lgkmcnt(9)
	v_mfma_f32_16x16x32_bf16 v[200:203], v[76:79], v[32:35], v[200:203]
	v_cvt_pk_bf16_f32 v216, v232, v233
	v_cvt_pk_bf16_f32 v217, v234, v235
	v_cvt_pk_bf16_f32 v218, v236, v237
	v_cvt_pk_bf16_f32 v219, v238, v239
	s_waitcnt lgkmcnt(8)
	v_mfma_f32_16x16x32_bf16 v[204:207], v[80:83], v[32:35], v[204:207]
	v_sub_f32_e32 v240, v240, v184
	v_sub_f32_e32 v241, v241, v185
	v_sub_f32_e32 v242, v242, v186
	v_sub_f32_e32 v243, v243, v187
	v_sub_f32_e32 v244, v244, v188
	v_sub_f32_e32 v245, v245, v189
	v_sub_f32_e32 v246, v246, v190
	v_sub_f32_e32 v247, v247, v191
	ds_read_b128 v[128:131], v51 offset:32768
	ds_read_b128 v[132:135], v51 offset:33792
	ds_read_b128 v[136:139], v51 offset:34816
	ds_read_b128 v[140:143], v51 offset:35840
	ds_read_b128 v[144:147], v51 offset:36864
	ds_read_b128 v[148:151], v51 offset:37888
	s_waitcnt lgkmcnt(13)
	v_mfma_f32_16x16x32_bf16 v[192:195], v[84:87], v[216:219], v[192:195]
	v_cvt_pk_bf16_f32 v220, v240, v241
	v_cvt_pk_bf16_f32 v221, v242, v243
	s_waitcnt lgkmcnt(12)
	v_mfma_f32_16x16x32_bf16 v[196:199], v[88:91], v[216:219], v[196:199]
	v_cvt_pk_bf16_f32 v222, v244, v245
	v_cvt_pk_bf16_f32 v223, v246, v247
	s_waitcnt lgkmcnt(11)
	v_mfma_f32_16x16x32_bf16 v[200:203], v[92:95], v[216:219], v[200:203]
	ds_read_b128 v[152:155], v51 offset:38912
	s_waitcnt lgkmcnt(11)
	v_mfma_f32_16x16x32_bf16 v[204:207], v[96:99], v[216:219], v[204:207]
	ds_read_b128 v[156:159], v51 offset:39936
	s_waitcnt lgkmcnt(11)
	v_mfma_f32_16x16x32_bf16 v[192:195], v[100:103], v[220:223], v[192:195]
	s_waitcnt lgkmcnt(10)
	v_mfma_f32_16x16x32_bf16 v[196:199], v[104:107], v[220:223], v[196:199]
	s_waitcnt lgkmcnt(9)
	v_mfma_f32_16x16x32_bf16 v[200:203], v[108:111], v[220:223], v[200:203]
	s_waitcnt lgkmcnt(8)
	v_mfma_f32_16x16x32_bf16 v[204:207], v[112:115], v[220:223], v[204:207]
	ds_read_b128 v[160:163], v51 offset:40960
	ds_read_b128 v[164:167], v51 offset:41984
	ds_read_b128 v[172:175], v51 offset:43008
	ds_read_b128 v[248:251], v51 offset:44032
	ds_read_b128 v[232:235], v51 offset:45056
	ds_read_b128 v[236:239], v51 offset:46080
	ds_read_b128 v[240:243], v51 offset:47104
	s_add_i32 s0, s0, 1
	s_and_b32 s1, s0, 1
	s_lshl_b32 s8, s1, 16
	s_lshl_b32 s1, s1, 2
	s_add_i32 s9, s8, s79
	s_add_i32 s1, s1, 0x20000
	s_waitcnt lgkmcnt(14)
	v_mfma_f32_16x16x32_bf16 v[0:3], v[128:131], v[216:219], v[0:3]
	ds_read_b128 v[244:247], v51 offset:48128
	s_waitcnt lgkmcnt(14)
	v_mfma_f32_16x16x32_bf16 v[0:3], v[132:135], v[220:223], v[0:3]
	v_add_u32_e32 v50, s9, v124
	v_mov_b32_e32 v214, s1
	s_waitcnt lgkmcnt(13)
	v_mfma_f32_16x16x32_bf16 v[4:7], v[136:139], v[216:219], v[4:7]
	s_waitcnt lgkmcnt(12)
	v_mfma_f32_16x16x32_bf16 v[4:7], v[140:143], v[220:223], v[4:7]
	v_cvt_pk_bf16_f32 v224, v192, v193
	v_cvt_pk_bf16_f32 v225, v194, v195
	v_cvt_pk_bf16_f32 v226, v196, v197
	v_cvt_pk_bf16_f32 v227, v198, v199
	s_waitcnt lgkmcnt(11)
	v_mfma_f32_16x16x32_bf16 v[8:11], v[144:147], v[216:219], v[8:11]
	s_waitcnt lgkmcnt(10)
	v_mfma_f32_16x16x32_bf16 v[8:11], v[148:151], v[220:223], v[8:11]
	v_cvt_pk_bf16_f32 v228, v200, v201
	v_cvt_pk_bf16_f32 v229, v202, v203
	v_cvt_pk_bf16_f32 v230, v204, v205
	v_cvt_pk_bf16_f32 v231, v206, v207
	global_store_dwordx4 v[48:49], v[224:227], off
	s_waitcnt lgkmcnt(9)
	v_mfma_f32_16x16x32_bf16 v[12:15], v[152:155], v[216:219], v[12:15]
	v_cvt_pk_bf16_f32 v44, v0, v1
	v_cvt_pk_bf16_f32 v45, v2, v3
	v_cvt_pk_bf16_f32 v46, v4, v5
	v_cvt_pk_bf16_f32 v47, v6, v7
	global_store_dwordx4 v[48:49], v[228:231], off offset:16
	v_add_u32_e32 v51, s8, v120
	s_mov_b64 s[8:9], 0x68000
	v_lshl_add_u64 v[48:49], v[48:49], 0, s[8:9]
	s_cmpk_lg_i32 s0, 0x100
	s_waitcnt lgkmcnt(0)
	v_mfma_f32_16x16x32_bf16 v[12:15], v[156:159], v[220:223], v[12:15]
	s_barrier
	s_cbranch_scc1 .LBB0_1548
	s_mov_b64 s[0:1], 0
